# grid barriers b1-b11: the leader completing the top level bumps all per-XCD generation words itself (no relay by the other XCD leaders)
# speedup vs baseline: 1.0047x; 1.0047x over previous
; __device__ __forceinline__ unsigned xb_ld(unsigned* p) { return __hip_atomic_load(p, __ATOMIC_RELAXED, __HIP_MEMORY_SCOPE_AGENT); }
; __device__ __forceinline__ unsigned xb_add(unsigned* p, unsigned v) { return __hip_atomic_fetch_add(p, v, __ATOMIC_RELAXED, __HIP_MEMORY_SCOPE_AGENT); }
; #define XB_SPIN(cond, bar) do { unsigned _sp = 0; while (cond) { __builtin_amdgcn_s_sleep(1); \
;     if ((++_sp & 255u) == 0u) { if (xb_ld(&(bar)[XB_TMO])) break; if (_sp > XB_SPIN_CAP) { atomicAdd(&(bar)[XB_TMO], 1u); break; } } } } while (0)
; __device__ __forceinline__ void xcd_barrier(const Params& P, volatile LAS unsigned* st, const int wvi) {
;     ...
;     const unsigned old = xb_add(&bar[XB_XSUB(b.x)], 1u);
;     const unsigned gen = old / nloc;
;     if (old + 1u == (gen + 1u) * nloc) {
;       __builtin_amdgcn_fence(__ATOMIC_RELEASE, "agent");
;       asm volatile("s_waitcnt vmcnt(0)" ::: "memory");
;       const unsigned og = xb_add(&bar[XB_TOP], 1u);
;       const unsigned tg = og / nx;
;       if (og + 1u == (tg + 1u) * nx) xb_add(&bar[XB_TOPGEN], 1u);
;       else XB_SPIN(xb_ld(&bar[XB_TOPGEN]) == tg, bar);
;       __builtin_amdgcn_fence(__ATOMIC_ACQUIRE, "agent");
;       xb_add(&bar[XB_XGEN(b.x)], 1u);
.LBB0_156:
	s_or_b64 exec, exec, s[6:7]
	v_cvt_f32_u32_e32 v3, v0
	s_waitcnt vmcnt(0)
	v_readfirstlane_b32 s4, v2
	v_sub_u32_e32 v2, 0, v0
	s_mov_b64 s[6:7], -1
	v_rcp_iflag_f32_e32 v3, v3
	v_add_u32_e32 v1, s4, v1
	v_add_u32_e32 v4, 1, v1
	v_readlane_b32 s4, v246, 46
	v_mul_f32_e32 v3, 0x4f7ffffe, v3
	v_cvt_u32_f32_e32 v3, v3
	v_readlane_b32 s5, v246, 47
	v_mul_lo_u32 v2, v2, v3
	v_mul_hi_u32 v2, v3, v2
	v_add_u32_e32 v2, v3, v2
	v_mul_hi_u32 v2, v1, v2
	v_mul_lo_u32 v3, v2, v0
	v_sub_u32_e32 v1, v1, v3
	v_add_u32_e32 v5, 1, v2
	v_sub_u32_e32 v3, v1, v0
	v_cmp_ge_u32_e32 vcc, v1, v0
	s_nop 1
	v_cndmask_b32_e32 v2, v2, v5, vcc
	v_cndmask_b32_e32 v1, v1, v3, vcc
	v_add_u32_e32 v3, 1, v2
	v_cmp_ge_u32_e32 vcc, v1, v0
	s_nop 1
	v_cndmask_b32_e32 v2, v2, v3, vcc
	v_mul_lo_u32 v1, v0, v2
	v_add_u32_e32 v0, v1, v0
	v_cmp_ne_u32_e32 vcc, v4, v0
	v_mov_b64_e32 v[0:1], s[4:5]
	s_cbranch_vccnz .Lbar1_nl
	v_readlane_b32 s8, v246, 7
	v_readlane_b32 s9, v246, 8
	s_nop 1
	s_add_u32 s10, s8, 0x800
	s_addc_u32 s11, s9, 0
	s_nop 3
	global_atomic_add v196, v197, s[8:9] offset:1024
	global_atomic_add v196, v197, s[8:9] offset:1280
	global_atomic_add v196, v197, s[8:9] offset:1536
	global_atomic_add v196, v197, s[8:9] offset:1792
	global_atomic_add v196, v197, s[8:9] offset:2048
	global_atomic_add v196, v197, s[8:9] offset:2304
	global_atomic_add v196, v197, s[8:9] offset:2560
	global_atomic_add v196, v197, s[8:9] offset:2816
	global_atomic_add v196, v197, s[10:11] offset:1024
	global_atomic_add v196, v197, s[10:11] offset:1280
	global_atomic_add v196, v197, s[10:11] offset:1536
	global_atomic_add v196, v197, s[10:11] offset:1792
	global_atomic_add v196, v197, s[10:11] offset:2048
	global_atomic_add v196, v197, s[10:11] offset:2304
	global_atomic_add v196, v197, s[10:11] offset:2560
	global_atomic_add v196, v197, s[10:11] offset:2816
.Lbar1_nl:
	s_and_saveexec_b64 s[4:5], vcc
	s_cbranch_execz .LBB0_168
	v_readlane_b32 s6, v246, 46
	v_readlane_b32 s7, v246, 47
	s_mov_b64 s[8:9], 0
	s_nop 3
	global_load_dword v0, v145, s[6:7] sc1
	s_waitcnt vmcnt(0)
	v_cmp_eq_u32_e32 vcc, v0, v2
	s_and_saveexec_b64 s[6:7], vcc
	s_cbranch_execz .LBB0_167
	s_mov_b32 s18, 1
	s_branch .LBB0_160

; __device__ __forceinline__ unsigned xb_add(unsigned* p, unsigned v) { return __hip_atomic_fetch_add(p, v, __ATOMIC_RELAXED, __HIP_MEMORY_SCOPE_AGENT); }
; __device__ __forceinline__ void xcd_barrier(const Params& P, volatile LAS unsigned* st, const int wvi) {
;     ...
;       __builtin_amdgcn_fence(__ATOMIC_ACQUIRE, "agent");
;       xb_add(&bar[XB_XGEN(b.x)], 1u);
.LBB0_170:
	s_or_b64 exec, exec, s[4:5]
	s_mov_b64 s[4:5], exec
	v_mbcnt_lo_u32_b32 v0, s4, 0
	v_mbcnt_hi_u32_b32 v0, s5, v0
	v_cmp_eq_u32_e32 vcc, 0, v0
	s_waitcnt vmcnt(0)
	buffer_inv sc1
	s_and_saveexec_b64 s[6:7], vcc
	s_cbranch_execz .LBB0_172
	s_bcnt1_i32_b64 s4, s[4:5]
	v_mov_b32_e32 v0, s4
.LBB0_172:
	s_or_b64 exec, exec, s[6:7]
	s_waitcnt vmcnt(0)

; __device__ __forceinline__ unsigned xb_ld(unsigned* p) { return __hip_atomic_load(p, __ATOMIC_RELAXED, __HIP_MEMORY_SCOPE_AGENT); }
; __device__ __forceinline__ unsigned xb_add(unsigned* p, unsigned v) { return __hip_atomic_fetch_add(p, v, __ATOMIC_RELAXED, __HIP_MEMORY_SCOPE_AGENT); }
; #define XB_SPIN(cond, bar) do { unsigned _sp = 0; while (cond) { __builtin_amdgcn_s_sleep(1); \
;     if ((++_sp & 255u) == 0u) { if (xb_ld(&(bar)[XB_TMO])) break; if (_sp > XB_SPIN_CAP) { atomicAdd(&(bar)[XB_TMO], 1u); break; } } } } while (0)
; __device__ __forceinline__ void xcd_barrier(const Params& P, volatile LAS unsigned* st, const int wvi) {
;     ...
;     const unsigned old = xb_add(&bar[XB_XSUB(b.x)], 1u);
;     const unsigned gen = old / nloc;
;     if (old + 1u == (gen + 1u) * nloc) {
;       __builtin_amdgcn_fence(__ATOMIC_RELEASE, "agent");
;       asm volatile("s_waitcnt vmcnt(0)" ::: "memory");
;       const unsigned og = xb_add(&bar[XB_TOP], 1u);
;       const unsigned tg = og / nx;
;       if (og + 1u == (tg + 1u) * nx) xb_add(&bar[XB_TOPGEN], 1u);
;       else XB_SPIN(xb_ld(&bar[XB_TOPGEN]) == tg, bar);
.LBB0_305:
	s_or_b64 exec, exec, s[6:7]
	s_waitcnt vmcnt(0)
	v_readfirstlane_b32 s4, v2
	v_cvt_f32_u32_e32 v2, v0
	v_sub_u32_e32 v3, 0, v0
	v_add_u32_e32 v1, s4, v1
	v_readlane_b32 s4, v246, 46
	v_rcp_iflag_f32_e32 v2, v2
	v_readlane_b32 s5, v246, 47
	s_mov_b64 s[6:7], -1
	v_mul_f32_e32 v2, 0x4f7ffffe, v2
	v_cvt_u32_f32_e32 v2, v2
	v_mul_lo_u32 v3, v3, v2
	v_mul_hi_u32 v3, v2, v3
	v_add_u32_e32 v2, v2, v3
	v_mul_hi_u32 v2, v1, v2
	v_mul_lo_u32 v3, v2, v0
	v_sub_u32_e32 v3, v1, v3
	v_cmp_ge_u32_e32 vcc, v3, v0
	v_add_u32_e32 v4, 1, v2
	v_add_u32_e32 v1, 1, v1
	v_cndmask_b32_e32 v2, v2, v4, vcc
	v_sub_u32_e32 v4, v3, v0
	v_cndmask_b32_e32 v3, v3, v4, vcc
	v_cmp_ge_u32_e32 vcc, v3, v0
	v_add_u32_e32 v3, 1, v2
	s_nop 0
	v_cndmask_b32_e32 v2, v2, v3, vcc
	v_mul_lo_u32 v3, v0, v2
	v_add_u32_e32 v0, v3, v0
	v_cmp_ne_u32_e32 vcc, v1, v0
	v_mov_b64_e32 v[0:1], s[4:5]
	s_cbranch_vccnz .Lbar2_nl
	v_readlane_b32 s8, v246, 7
	v_readlane_b32 s9, v246, 8
	s_nop 1
	s_add_u32 s10, s8, 0x800
	s_addc_u32 s11, s9, 0
	s_nop 3
	global_atomic_add v196, v197, s[8:9] offset:1024
	global_atomic_add v196, v197, s[8:9] offset:1280
	global_atomic_add v196, v197, s[8:9] offset:1536
	global_atomic_add v196, v197, s[8:9] offset:1792
	global_atomic_add v196, v197, s[8:9] offset:2048
	global_atomic_add v196, v197, s[8:9] offset:2304
	global_atomic_add v196, v197, s[8:9] offset:2560
	global_atomic_add v196, v197, s[8:9] offset:2816
	global_atomic_add v196, v197, s[10:11] offset:1024
	global_atomic_add v196, v197, s[10:11] offset:1280
	global_atomic_add v196, v197, s[10:11] offset:1536
	global_atomic_add v196, v197, s[10:11] offset:1792
	global_atomic_add v196, v197, s[10:11] offset:2048
	global_atomic_add v196, v197, s[10:11] offset:2304
	global_atomic_add v196, v197, s[10:11] offset:2560
	global_atomic_add v196, v197, s[10:11] offset:2816

; __device__ __forceinline__ unsigned xb_add(unsigned* p, unsigned v) { return __hip_atomic_fetch_add(p, v, __ATOMIC_RELAXED, __HIP_MEMORY_SCOPE_AGENT); }
; __device__ __forceinline__ void xcd_barrier(const Params& P, volatile LAS unsigned* st, const int wvi) {
;     ...
;       __builtin_amdgcn_fence(__ATOMIC_ACQUIRE, "agent");
;       xb_add(&bar[XB_XGEN(b.x)], 1u);
.LBB0_319:
	s_or_b64 exec, exec, s[4:5]
	s_mov_b64 s[4:5], exec
	v_mbcnt_lo_u32_b32 v0, s4, 0
	v_mbcnt_hi_u32_b32 v0, s5, v0
	v_cmp_eq_u32_e32 vcc, 0, v0
	s_waitcnt vmcnt(0)
	buffer_inv sc1
	s_and_saveexec_b64 s[6:7], vcc
	s_cbranch_execz .LBB0_321
	s_bcnt1_i32_b64 s4, s[4:5]
	v_mov_b32_e32 v0, s4
.LBB0_321:
	s_or_b64 exec, exec, s[6:7]
	s_waitcnt vmcnt(0)

; __device__ __forceinline__ unsigned xb_add(unsigned* p, unsigned v) { return __hip_atomic_fetch_add(p, v, __ATOMIC_RELAXED, __HIP_MEMORY_SCOPE_AGENT); }
; __device__ __forceinline__ void xcd_barrier(const Params& P, volatile LAS unsigned* st, const int wvi) {
;     ...
;       __builtin_amdgcn_fence(__ATOMIC_ACQUIRE, "agent");
;       xb_add(&bar[XB_XGEN(b.x)], 1u);
.LBB0_377:
	s_or_b64 exec, exec, s[4:5]
	s_mov_b64 s[4:5], exec
	v_mbcnt_lo_u32_b32 v0, s4, 0
	v_mbcnt_hi_u32_b32 v0, s5, v0
	v_cmp_eq_u32_e32 vcc, 0, v0
	s_waitcnt vmcnt(0)
	buffer_inv sc1
	s_and_saveexec_b64 s[6:7], vcc
	s_cbranch_execz .LBB0_379
	s_bcnt1_i32_b64 s4, s[4:5]
	v_mov_b32_e32 v0, s4
.LBB0_379:
	s_or_b64 exec, exec, s[6:7]
	s_waitcnt vmcnt(0)

; __device__ __forceinline__ unsigned xb_add(unsigned* p, unsigned v) { return __hip_atomic_fetch_add(p, v, __ATOMIC_RELAXED, __HIP_MEMORY_SCOPE_AGENT); }
; __device__ __forceinline__ void xcd_barrier(const Params& P, volatile LAS unsigned* st, const int wvi) {
;     ...
;       __builtin_amdgcn_fence(__ATOMIC_ACQUIRE, "agent");
;       xb_add(&bar[XB_XGEN(b.x)], 1u);
.LBB0_432:
	s_or_b64 exec, exec, s[4:5]
	s_mov_b64 s[4:5], exec
	v_mbcnt_lo_u32_b32 v0, s4, 0
	v_mbcnt_hi_u32_b32 v0, s5, v0
	v_cmp_eq_u32_e32 vcc, 0, v0
	s_waitcnt vmcnt(0)
	buffer_inv sc1
	s_and_saveexec_b64 s[6:7], vcc
	s_cbranch_execz .LBB0_434
	s_bcnt1_i32_b64 s4, s[4:5]
	v_mov_b32_e32 v0, s4
.LBB0_434:
	s_or_b64 exec, exec, s[6:7]
	s_waitcnt vmcnt(0)

; __device__ __forceinline__ unsigned xb_ld(unsigned* p) { return __hip_atomic_load(p, __ATOMIC_RELAXED, __HIP_MEMORY_SCOPE_AGENT); }
; __device__ __forceinline__ unsigned xb_add(unsigned* p, unsigned v) { return __hip_atomic_fetch_add(p, v, __ATOMIC_RELAXED, __HIP_MEMORY_SCOPE_AGENT); }
; #define XB_SPIN(cond, bar) do { unsigned _sp = 0; while (cond) { __builtin_amdgcn_s_sleep(1); \
;     if ((++_sp & 255u) == 0u) { if (xb_ld(&(bar)[XB_TMO])) break; if (_sp > XB_SPIN_CAP) { atomicAdd(&(bar)[XB_TMO], 1u); break; } } } } while (0)
; __device__ __forceinline__ void xcd_barrier(const Params& P, volatile LAS unsigned* st, const int wvi) {
;     ...
;     const unsigned old = xb_add(&bar[XB_XSUB(b.x)], 1u);
;     const unsigned gen = old / nloc;
;     if (old + 1u == (gen + 1u) * nloc) {
;       __builtin_amdgcn_fence(__ATOMIC_RELEASE, "agent");
;       asm volatile("s_waitcnt vmcnt(0)" ::: "memory");
;       const unsigned og = xb_add(&bar[XB_TOP], 1u);
;       const unsigned tg = og / nx;
;       if (og + 1u == (tg + 1u) * nx) xb_add(&bar[XB_TOPGEN], 1u);
;       else XB_SPIN(xb_ld(&bar[XB_TOPGEN]) == tg, bar);
.LBB0_728:
	s_or_b64 exec, exec, s[6:7]
	s_waitcnt vmcnt(0)
	v_readfirstlane_b32 s4, v2
	v_cvt_f32_u32_e32 v2, v0
	v_sub_u32_e32 v3, 0, v0
	v_add_u32_e32 v1, s4, v1
	v_readlane_b32 s4, v244, 1
	v_rcp_iflag_f32_e32 v2, v2
	v_readlane_b32 s5, v244, 2
	s_mov_b64 s[6:7], -1
	v_mul_f32_e32 v2, 0x4f7ffffe, v2
	v_cvt_u32_f32_e32 v2, v2
	v_mul_lo_u32 v3, v3, v2
	v_mul_hi_u32 v3, v2, v3
	v_add_u32_e32 v2, v2, v3
	v_mul_hi_u32 v2, v1, v2
	v_mul_lo_u32 v3, v2, v0
	v_sub_u32_e32 v3, v1, v3
	v_cmp_ge_u32_e32 vcc, v3, v0
	v_add_u32_e32 v4, 1, v2
	v_add_u32_e32 v1, 1, v1
	v_cndmask_b32_e32 v2, v2, v4, vcc
	v_sub_u32_e32 v4, v3, v0
	v_cndmask_b32_e32 v3, v3, v4, vcc
	v_cmp_ge_u32_e32 vcc, v3, v0
	v_add_u32_e32 v3, 1, v2
	s_nop 0
	v_cndmask_b32_e32 v2, v2, v3, vcc
	v_mul_lo_u32 v3, v0, v2
	v_add_u32_e32 v0, v3, v0
	v_cmp_ne_u32_e32 vcc, v1, v0
	v_mov_b64_e32 v[0:1], s[4:5]
	s_cbranch_vccnz .Lbar5_nl
	v_readlane_b32 s8, v245, 27
	v_readlane_b32 s9, v245, 28
	s_nop 1
	s_add_u32 s10, s8, 0x800
	s_addc_u32 s11, s9, 0
	s_nop 3
	global_atomic_add v196, v197, s[8:9] offset:1024
	global_atomic_add v196, v197, s[8:9] offset:1280
	global_atomic_add v196, v197, s[8:9] offset:1536
	global_atomic_add v196, v197, s[8:9] offset:1792
	global_atomic_add v196, v197, s[8:9] offset:2048
	global_atomic_add v196, v197, s[8:9] offset:2304
	global_atomic_add v196, v197, s[8:9] offset:2560
	global_atomic_add v196, v197, s[8:9] offset:2816
	global_atomic_add v196, v197, s[10:11] offset:1024
	global_atomic_add v196, v197, s[10:11] offset:1280
	global_atomic_add v196, v197, s[10:11] offset:1536
	global_atomic_add v196, v197, s[10:11] offset:1792
	global_atomic_add v196, v197, s[10:11] offset:2048
	global_atomic_add v196, v197, s[10:11] offset:2304
	global_atomic_add v196, v197, s[10:11] offset:2560
	global_atomic_add v196, v197, s[10:11] offset:2816
.Lbar5_nl:
	s_and_saveexec_b64 s[4:5], vcc
	s_cbranch_execz .LBB0_740
	v_readlane_b32 s6, v244, 1
	v_readlane_b32 s7, v244, 2
	s_mov_b64 s[8:9], 0
	s_nop 3
	global_load_dword v0, v145, s[6:7] sc1
	s_waitcnt vmcnt(0)
	v_cmp_eq_u32_e32 vcc, v0, v2
	s_and_saveexec_b64 s[6:7], vcc
	s_cbranch_execz .LBB0_739
	s_mov_b32 s18, 1
	s_branch .LBB0_732

; __device__ __forceinline__ unsigned xb_add(unsigned* p, unsigned v) { return __hip_atomic_fetch_add(p, v, __ATOMIC_RELAXED, __HIP_MEMORY_SCOPE_AGENT); }
; __device__ __forceinline__ void xcd_barrier(const Params& P, volatile LAS unsigned* st, const int wvi) {
;     ...
;       __builtin_amdgcn_fence(__ATOMIC_ACQUIRE, "agent");
;       xb_add(&bar[XB_XGEN(b.x)], 1u);
.LBB0_742:
	s_or_b64 exec, exec, s[4:5]
	s_mov_b64 s[4:5], exec
	v_mbcnt_lo_u32_b32 v0, s4, 0
	v_mbcnt_hi_u32_b32 v0, s5, v0
	v_cmp_eq_u32_e32 vcc, 0, v0
	s_waitcnt vmcnt(0)
	buffer_inv sc1
	s_and_saveexec_b64 s[6:7], vcc
	s_cbranch_execz .LBB0_744
	s_bcnt1_i32_b64 s4, s[4:5]
	v_mov_b32_e32 v0, s4
.LBB0_744:
	s_or_b64 exec, exec, s[6:7]
	s_waitcnt vmcnt(0)

; __device__ __forceinline__ unsigned xb_add(unsigned* p, unsigned v) { return __hip_atomic_fetch_add(p, v, __ATOMIC_RELAXED, __HIP_MEMORY_SCOPE_AGENT); }
; __device__ __forceinline__ void xcd_barrier(const Params& P, volatile LAS unsigned* st, const int wvi) {
;     ...
;       __builtin_amdgcn_fence(__ATOMIC_ACQUIRE, "agent");
;       xb_add(&bar[XB_XGEN(b.x)], 1u);
.LBB0_797:
	s_or_b64 exec, exec, s[4:5]
	s_mov_b64 s[4:5], exec
	v_mbcnt_lo_u32_b32 v0, s4, 0
	v_mbcnt_hi_u32_b32 v0, s5, v0
	v_cmp_eq_u32_e32 vcc, 0, v0
	s_waitcnt vmcnt(0)
	buffer_inv sc1
	s_and_saveexec_b64 s[6:7], vcc
	s_cbranch_execz .LBB0_799
	s_bcnt1_i32_b64 s4, s[4:5]
	v_mov_b32_e32 v0, s4
.LBB0_799:
	s_or_b64 exec, exec, s[6:7]
	s_waitcnt vmcnt(0)

; __device__ __forceinline__ unsigned xb_add(unsigned* p, unsigned v) { return __hip_atomic_fetch_add(p, v, __ATOMIC_RELAXED, __HIP_MEMORY_SCOPE_AGENT); }
; __device__ __forceinline__ void xcd_barrier(const Params& P, volatile LAS unsigned* st, const int wvi) {
;     ...
;       __builtin_amdgcn_fence(__ATOMIC_ACQUIRE, "agent");
;       xb_add(&bar[XB_XGEN(b.x)], 1u);
.LBB0_879:
	s_or_b64 exec, exec, s[4:5]
	s_mov_b64 s[4:5], exec
	v_mbcnt_lo_u32_b32 v0, s4, 0
	v_mbcnt_hi_u32_b32 v0, s5, v0
	v_cmp_eq_u32_e32 vcc, 0, v0
	s_waitcnt vmcnt(0)
	buffer_inv sc1
	s_and_saveexec_b64 s[6:7], vcc
	s_cbranch_execz .LBB0_881
	s_bcnt1_i32_b64 s4, s[4:5]
	v_mov_b32_e32 v0, s4
.LBB0_881:
	s_or_b64 exec, exec, s[6:7]
	s_waitcnt vmcnt(0)

; __device__ __forceinline__ unsigned xb_add(unsigned* p, unsigned v) { return __hip_atomic_fetch_add(p, v, __ATOMIC_RELAXED, __HIP_MEMORY_SCOPE_AGENT); }
; __device__ __forceinline__ void xcd_barrier(const Params& P, volatile LAS unsigned* st, const int wvi) {
;     ...
;       __builtin_amdgcn_fence(__ATOMIC_ACQUIRE, "agent");
;       xb_add(&bar[XB_XGEN(b.x)], 1u);
.LBB0_947:
	s_or_b64 exec, exec, s[4:5]
	s_mov_b64 s[4:5], exec
	v_mbcnt_lo_u32_b32 v0, s4, 0
	v_mbcnt_hi_u32_b32 v0, s5, v0
	v_cmp_eq_u32_e32 vcc, 0, v0
	s_waitcnt vmcnt(0)
	buffer_inv sc1
	s_and_saveexec_b64 s[6:7], vcc
	s_cbranch_execz .LBB0_949
	s_bcnt1_i32_b64 s4, s[4:5]
	v_mov_b32_e32 v0, s4
.LBB0_949:
	s_or_b64 exec, exec, s[6:7]
	s_waitcnt vmcnt(0)

; __device__ __forceinline__ unsigned xb_add(unsigned* p, unsigned v) { return __hip_atomic_fetch_add(p, v, __ATOMIC_RELAXED, __HIP_MEMORY_SCOPE_AGENT); }
; __device__ __forceinline__ void xcd_barrier(const Params& P, volatile LAS unsigned* st, const int wvi) {
;     ...
;       __builtin_amdgcn_fence(__ATOMIC_ACQUIRE, "agent");
;       xb_add(&bar[XB_XGEN(b.x)], 1u);
.LBB0_1002:
	s_or_b64 exec, exec, s[4:5]
	s_mov_b64 s[4:5], exec
	v_mbcnt_lo_u32_b32 v0, s4, 0
	v_mbcnt_hi_u32_b32 v0, s5, v0
	v_cmp_eq_u32_e32 vcc, 0, v0
	s_waitcnt vmcnt(0)
	buffer_inv sc1
	s_and_saveexec_b64 s[6:7], vcc
	s_cbranch_execz .LBB0_1004
	s_bcnt1_i32_b64 s4, s[4:5]
	v_mov_b32_e32 v0, s4
.LBB0_1004:
	s_or_b64 exec, exec, s[6:7]
	s_waitcnt vmcnt(0)

; __device__ __forceinline__ unsigned xb_add(unsigned* p, unsigned v) { return __hip_atomic_fetch_add(p, v, __ATOMIC_RELAXED, __HIP_MEMORY_SCOPE_AGENT); }
; __device__ __forceinline__ void xcd_barrier(const Params& P, volatile LAS unsigned* st, const int wvi) {
;     ...
;       __builtin_amdgcn_fence(__ATOMIC_ACQUIRE, "agent");
;       xb_add(&bar[XB_XGEN(b.x)], 1u);
.LBB0_1070:
	s_or_b64 exec, exec, s[4:5]
	s_mov_b64 s[4:5], exec
	v_mbcnt_lo_u32_b32 v0, s4, 0
	v_mbcnt_hi_u32_b32 v0, s5, v0
	v_cmp_eq_u32_e32 vcc, 0, v0
	s_waitcnt vmcnt(0)
	buffer_inv sc1
	s_and_saveexec_b64 s[6:7], vcc
	s_cbranch_execz .LBB0_1072
	s_bcnt1_i32_b64 s4, s[4:5]
	v_mov_b32_e32 v0, s4
.LBB0_1072:
	s_or_b64 exec, exec, s[6:7]
	s_waitcnt vmcnt(0)

; __device__ __forceinline__ unsigned xb_add(unsigned* p, unsigned v) { return __hip_atomic_fetch_add(p, v, __ATOMIC_RELAXED, __HIP_MEMORY_SCOPE_AGENT); }
; __device__ __forceinline__ void xcd_barrier(const Params& P, volatile LAS unsigned* st, const int wvi) {
;     ...
;       __builtin_amdgcn_fence(__ATOMIC_ACQUIRE, "agent");
;       xb_add(&bar[XB_XGEN(b.x)], 1u);
.LBB0_1137:
	s_or_b64 exec, exec, s[4:5]
	s_mov_b64 s[4:5], exec
	v_mbcnt_lo_u32_b32 v0, s4, 0
	v_mbcnt_hi_u32_b32 v0, s5, v0
	v_cmp_eq_u32_e32 vcc, 0, v0
	s_waitcnt vmcnt(0)
	buffer_inv sc1
	s_and_saveexec_b64 s[6:7], vcc
	s_cbranch_execz .LBB0_1139
	s_bcnt1_i32_b64 s4, s[4:5]
	v_mov_b32_e32 v0, s4
.LBB0_1139:
	s_or_b64 exec, exec, s[6:7]
	s_waitcnt vmcnt(0)
